# sample_gemm K-loop: A/B chunks staged once per workgroup through LDS (double buffered, prefetched) instead of per-wave global fragment loads
# speedup vs baseline: 1.1309x; 1.0418x over previous
.LBB0_683:
	v_readfirstlane_b32 s98, v38
	v_readfirstlane_b32 s99, v39
	v_readfirstlane_b32 s100, v40
	v_readfirstlane_b32 s101, v41
	v_readlane_b32 vcc_lo, v252, 60
	s_lshr_b32 vcc_lo, vcc_lo, 3
	s_and_b32 s40, vcc_lo, 1
	s_lshl_b32 s41, s36, 4
	s_mul_i32 s40, s40, s41
	s_sub_u32 s98, s98, s40
	s_subb_u32 s99, s99, 0
	s_lshr_b32 s40, vcc_lo, 1
	s_lshl_b32 s41, s20, 4
	s_mul_i32 s40, s40, s41
	s_add_u32 s40, s40, 0x100
	s_sub_u32 s100, s100, s40
	s_subb_u32 s101, s101, 0
	v_lshl_add_u32 v106, vcc_lo, 6, v162
	v_lshrrev_b32_e32 v107, 5, v106
	v_and_b32_e32 v108, 31, v106
	v_lshlrev_b32_e32 v108, 4, v108
	v_mov_b32_e32 v109, 0
	v_mov_b64_e32 v[112:113], s[98:99]
	v_lshl_add_u64 v[112:113], v[112:113], 0, v[108:109]
	v_mad_u64_u32 v[110:111], s[40:41], s36, v107, v[112:113]
	v_mov_b64_e32 v[112:113], s[100:101]
	v_lshl_add_u64 v[112:113], v[112:113], 0, v[108:109]
	v_mad_u64_u32 v[114:115], s[40:41], s20, v107, v[112:113]
	s_lshl_b32 s40, s36, 4
	s_mov_b32 s41, 0
	v_lshl_add_u64 v[116:117], v[110:111], 0, s[40:41]
	s_lshl_b32 s40, s20, 4
	v_lshl_add_u64 v[118:119], v[114:115], 0, s[40:41]
	v_lshl_add_u64 v[120:121], v[118:119], 0, s[40:41]
	v_lshl_add_u64 v[122:123], v[120:121], 0, s[40:41]
	v_mul_u32_u24_e32 v124, 0x210, v107
	v_add_u32_e32 v124, v124, v108
	v_and_b32_e32 v125, 15, v162
	v_lshrrev_b32_e32 v126, 4, v162
	s_and_b32 s40, vcc_lo, 1
	s_lshl_b32 s40, s40, 4
	v_add_u32_e32 v127, s40, v125
	v_mul_u32_u24_e32 v127, 0x210, v127
	v_lshl_add_u32 v127, v126, 4, v127
	s_lshr_b32 s40, vcc_lo, 1
	s_lshl_b32 s40, s40, 4
	v_add_u32_e32 v128, s40, v125
	v_mul_u32_u24_e32 v128, 0x210, v128
	v_lshl_add_u32 v128, v126, 4, v128
	v_add_u32_e32 v128, 0x4200, v128
	global_load_dwordx4 v[82:85], v[110:111], off
	global_load_dwordx4 v[86:89], v[116:117], off
	global_load_dwordx4 v[90:93], v[114:115], off
	global_load_dwordx4 v[94:97], v[118:119], off
	global_load_dwordx4 v[98:101], v[120:121], off
	global_load_dwordx4 v[102:105], v[122:123], off
	v_lshl_add_u64 v[110:111], v[110:111], 0, s[50:51]
	v_lshl_add_u64 v[116:117], v[116:117], 0, s[50:51]
	v_lshl_add_u64 v[114:115], v[114:115], 0, s[50:51]
	v_lshl_add_u64 v[118:119], v[118:119], 0, s[50:51]
	v_lshl_add_u64 v[120:121], v[120:121], 0, s[50:51]
	v_lshl_add_u64 v[122:123], v[122:123], 0, s[50:51]
	s_mov_b32 s40, 0
.Lsg_loop:
	v_add_u32_e32 v129, s40, v124
	s_waitcnt vmcnt(0)
	ds_write_b128 v129, v[82:85]
	ds_write_b128 v129, v[86:89] offset:8448
	ds_write_b128 v129, v[90:93] offset:16896
	ds_write_b128 v129, v[94:97] offset:25344
	ds_write_b128 v129, v[98:101] offset:33792
	ds_write_b128 v129, v[102:105] offset:42240
	s_addk_i32 s39, 0x100
	s_cmp_ge_u32 s39, s22
	s_cbranch_scc1 .Lsg_nopf
	global_load_dwordx4 v[82:85], v[110:111], off
	global_load_dwordx4 v[86:89], v[116:117], off
	global_load_dwordx4 v[90:93], v[114:115], off
	global_load_dwordx4 v[94:97], v[118:119], off
	global_load_dwordx4 v[98:101], v[120:121], off
	global_load_dwordx4 v[102:105], v[122:123], off
	v_lshl_add_u64 v[110:111], v[110:111], 0, s[50:51]
	v_lshl_add_u64 v[116:117], v[116:117], 0, s[50:51]
	v_lshl_add_u64 v[114:115], v[114:115], 0, s[50:51]
	v_lshl_add_u64 v[118:119], v[118:119], 0, s[50:51]
	v_lshl_add_u64 v[120:121], v[120:121], 0, s[50:51]
	v_lshl_add_u64 v[122:123], v[122:123], 0, s[50:51]
.Lsg_nopf:
	v_add_u32_e32 v130, s40, v127
	v_add_u32_e32 v131, s40, v128
	s_waitcnt lgkmcnt(0)
	s_barrier
	ds_read_b128 v[46:49], v130
	ds_read_b128 v[54:57], v131
	ds_read_b128 v[50:53], v130 offset:64
	ds_read_b128 v[58:61], v131 offset:64
	ds_read_b128 v[62:65], v130 offset:128
	ds_read_b128 v[66:69], v131 offset:128
	ds_read_b128 v[70:73], v130 offset:192
	ds_read_b128 v[74:77], v131 offset:192
	ds_read_b128 v[132:135], v130 offset:256
	ds_read_b128 v[148:151], v131 offset:256
	ds_read_b128 v[144:147], v130 offset:320
	ds_read_b128 v[152:155], v131 offset:320
	ds_read_b128 v[106:109], v130 offset:384
	ds_read_b128 v[156:159], v131 offset:384
	ds_read_b128 v[38:41], v130 offset:448
	ds_read_b128 v[78:81], v131 offset:448
	s_waitcnt lgkmcnt(14)
	v_mfma_f32_16x16x32_bf16 v[2:5], v[46:49], v[54:57], v[2:5]
	s_waitcnt lgkmcnt(12)
	v_mfma_f32_16x16x32_bf16 v[2:5], v[50:53], v[58:61], v[2:5]
	s_waitcnt lgkmcnt(10)
	v_mfma_f32_16x16x32_bf16 v[2:5], v[62:65], v[66:69], v[2:5]
	s_waitcnt lgkmcnt(8)
	v_mfma_f32_16x16x32_bf16 v[2:5], v[70:73], v[74:77], v[2:5]
	s_waitcnt lgkmcnt(6)
	v_mfma_f32_16x16x32_bf16 v[2:5], v[132:135], v[148:151], v[2:5]
	s_waitcnt lgkmcnt(4)
	v_mfma_f32_16x16x32_bf16 v[2:5], v[144:147], v[152:155], v[2:5]
	s_waitcnt lgkmcnt(2)
	v_mfma_f32_16x16x32_bf16 v[2:5], v[106:109], v[156:159], v[2:5]
	s_waitcnt lgkmcnt(0)
	v_mfma_f32_16x16x32_bf16 v[2:5], v[38:41], v[78:81], v[2:5]
	s_xor_b32 s40, s40, 0xc600
	s_cmp_ge_u32 s39, s22
	s_cbranch_scc0 .Lsg_loop
	s_barrier
	s_andn2_b64 vcc, exec, s[18:19]
	s_cbranch_vccnz .LBB0_686
	s_lshl_b32 s72, s5, 11
	v_lshl_add_u64 v[38:39], v[24:25], 0, s[72:73]
	v_lshl_add_u64 v[40:41], v[38:39], 0, v[26:27]
	v_lshl_add_u64 v[46:47], v[38:39], 0, v[28:29]
	global_load_ushort v40, v[40:41], off
	s_nop 0
	global_load_ushort v41, v[46:47], off
	s_waitcnt vmcnt(1)
	v_lshlrev_b32_e32 v40, 16, v40
	s_waitcnt vmcnt(0)
	v_lshlrev_b32_e32 v41, 16, v41
	v_pk_fma_f32 v[2:3], v[2:3], v[40:41], v[36:37]
	v_lshl_add_u64 v[36:37], v[38:39], 0, v[30:31]
	v_lshl_add_u64 v[38:39], v[38:39], 0, v[32:33]
	global_load_ushort v36, v[36:37], off
	s_nop 0
	global_load_ushort v37, v[38:39], off
	s_waitcnt vmcnt(1)
	v_lshlrev_b32_e32 v36, 16, v36
	s_waitcnt vmcnt(0)
	v_lshlrev_b32_e32 v37, 16, v37
	v_pk_fma_f32 v[4:5], v[4:5], v[36:37], v[34:35]
